# v13 plus QK K-fragment reads one step ahead in two extra buffers: 6 counted lgkmcnt waits per QK instead of 12
# baseline (speedup 1.0000x reference)
; #define SBAR() __builtin_amdgcn_sched_barrier(0)
; #define SLOAD(i, k0) do { st_[i].vs = *reinterpret_cast<const bf16x8*>(&Vh[(size_t)((k0) + sr) * LDK + sc]); \
;     st_[i].ks = *reinterpret_cast<const bf16x8*>(&Kh[(size_t)((k0) + sr) * LDK + sc]); \
;     if (DQ == 96) st_[i].kr = *reinterpret_cast<const bf16x8*>(&Kr[(size_t)((k0) + sr2) * 32 + sc2]); } while (0)
; #define SLOAD(i, k0) do { st_[i].vs = *reinterpret_cast<const bf16x8*>(&Vh[(size_t)((k0) + sr) * LDK + sc]); \
;     st_[i].ks = *reinterpret_cast<const bf16x8*>(&Kh[(size_t)((k0) + sr) * LDK + sc]); \
;     if (DQ == 96) st_[i].kr = *reinterpret_cast<const bf16x8*>(&Kr[(size_t)((k0) + sr2) * 32 + sc2]); } while (0)
; template <int DQ>
; __device__ __forceinline__ void qkt(f32x16& p0, f32x16& p1, const char* Ks, const bf16x8* qr, const f32x16& ci, int r32, int hi) {
;     constexpr int KROW = ACfg<DQ>::KROW;
; #pragma unroll
;     for (int d0 = 0; d0 < ACfg<DQ>::ND; ++d0) { const int cb = (d0 * 16 + hi * 8) * 2;
;         bf16x8 b0 = *reinterpret_cast<const bf16x8*>(Ks + r32 * KROW + cb);
;         bf16x8 b1 = *reinterpret_cast<const bf16x8*>(Ks + (32 + r32) * KROW + cb);
;         p0 = __builtin_amdgcn_mfma_f32_32x32x16_bf16(b0, qr[d0], d0 == 0 ? ci : p0, 0, 0, 0);
;         p1 = __builtin_amdgcn_mfma_f32_32x32x16_bf16(b1, qr[d0], d0 == 0 ? ci : p1, 0, 0, 0); }
; }
; template <int DQ, bool WIN, int LDQ, int LDK> ...
;     ...
;         SBAR(); qkt<DQ>(pA0, pA1, K_lds, qr, minit, r32, hi);
;         finish(pB0, pB1); SBAR();
;         if (j + 3 < NT) SLOAD(SE, KBASE(j + 3)); SBAR();
;         pv(vb0 + SHM_V);
.LBB0_1094:
	ds_read_b64_tr_b16 v[40:41], v194 offset:0
	ds_read_b64_tr_b16 v[42:43], v194 offset:0x400
	ds_read_b64_tr_b16 v[44:45], v194 offset:0x800
	ds_read_b64_tr_b16 v[46:47], v194 offset:0xc00
	ds_read_b128 v[80:83], v191 offset:29696
	ds_read_b128 v[198:201], v191 offset:36352
	ds_read_b128 v[202:205], v191 offset:29728
	ds_read_b128 v[212:215], v191 offset:36384
	v_exp_f32_e32 v72, v72
	v_exp_f32_e32 v73, v73
	v_exp_f32_e32 v74, v74
	s_waitcnt lgkmcnt(2)
	v_mfma_f32_32x32x16_bf16 v[96:111], v[80:83], v[134:137], v[48:63]
	v_exp_f32_e32 v75, v75
	v_exp_f32_e32 v197, v64
	v_exp_f32_e32 v206, v77
	v_exp_f32_e32 v207, v78
	v_exp_f32_e32 v208, v79
	v_mfma_f32_32x32x16_bf16 v[80:95], v[198:201], v[134:137], v[48:63]
	ds_read_b128 v[216:219], v191 offset:29760
	ds_read_b128 v[198:201], v191 offset:36416
	s_waitcnt lgkmcnt(2)
	v_mfma_f32_32x32x16_bf16 v[96:111], v[202:205], v[130:133], v[96:111]
	v_mfma_f32_32x32x16_bf16 v[80:95], v[212:215], v[130:133], v[80:95]
	ds_read_b128 v[202:205], v191 offset:29792
	ds_read_b128 v[212:215], v191 offset:36448
	s_waitcnt lgkmcnt(2)
	v_mfma_f32_32x32x16_bf16 v[96:111], v[216:219], v[126:129], v[96:111]
	v_mfma_f32_32x32x16_bf16 v[80:95], v[198:201], v[126:129], v[80:95]
	ds_read_b128 v[216:219], v191 offset:29824
	ds_read_b128 v[198:201], v191 offset:36480
	s_waitcnt lgkmcnt(2)
	v_mfma_f32_32x32x16_bf16 v[96:111], v[202:205], v[122:125], v[96:111]
	v_mfma_f32_32x32x16_bf16 v[80:95], v[212:215], v[122:125], v[80:95]
	ds_read_b128 v[202:205], v191 offset:29856
	ds_read_b128 v[212:215], v191 offset:36512
	s_waitcnt lgkmcnt(2)
	v_mfma_f32_32x32x16_bf16 v[96:111], v[216:219], v[118:121], v[96:111]
	v_mfma_f32_32x32x16_bf16 v[80:95], v[198:201], v[118:121], v[80:95]
	s_waitcnt lgkmcnt(0)
	v_mfma_f32_32x32x16_bf16 v[96:111], v[202:205], v[114:117], v[96:111]
	v_exp_f32_e32 v198, v65
	v_exp_f32_e32 v199, v66
	v_exp_f32_e32 v200, v67
	v_exp_f32_e32 v201, v68
	v_cvt_pk_bf16_f32 v68, v161, v196
	v_mfma_f32_32x32x16_bf16 v[80:95], v[212:215], v[114:117], v[80:95]
	v_exp_f32_e32 v202, v69
	v_exp_f32_e32 v203, v70
	v_exp_f32_e32 v204, v71
	v_exp_f32_e32 v205, v76
	v_cvt_pk_bf16_f32 v69, v158, v168
	v_cvt_pk_bf16_f32 v70, v159, v169
	v_cvt_pk_bf16_f32 v71, v160, v195
	v_cvt_pk_bf16_f32 v64, v150, v154
	v_cvt_pk_bf16_f32 v65, v151, v155
	v_cvt_pk_bf16_f32 v66, v152, v156
	v_cvt_pk_bf16_f32 v67, v153, v157
	v_cvt_pk_bf16_f32 v76, v197, v198
	v_cvt_pk_bf16_f32 v77, v199, v200
	v_cvt_pk_bf16_f32 v78, v201, v202
	v_cvt_pk_bf16_f32 v79, v203, v204
	v_cvt_pk_bf16_f32 v72, v72, v73
	v_cvt_pk_bf16_f32 v73, v74, v75
	v_cvt_pk_bf16_f32 v74, v205, v206
	v_cvt_pk_bf16_f32 v75, v207, v208
	v_lshl_add_u64 v[168:169], s[26:27], 0, v[164:165]
	s_mov_b32 s4, 0x218c0000
	v_add_co_u32_e32 v150, vcc, s4, v168
	s_nop 1
	v_addc_co_u32_e32 v151, vcc, 0, v169, vcc
	global_load_dwordx4 v[154:157], v[150:151], off offset:128
	global_load_dwordx4 v[158:161], v[150:151], off
	v_lshl_add_u64 v[150:151], s[26:27], 0, v[166:167]
	global_load_dwordx4 v[150:153], v[150:151], off
	ds_read_b64_tr_b16 v[204:205], v194 offset:0x1000
	ds_read_b64_tr_b16 v[206:207], v194 offset:0x1400
	ds_read_b64_tr_b16 v[208:209], v194 offset:0x1800
	ds_read_b64_tr_b16 v[210:211], v194 offset:0x1c00
	ds_read_b64_tr_b16 v[196:197], v194 offset:0x200
	ds_read_b64_tr_b16 v[198:199], v194 offset:0x600
	ds_read_b64_tr_b16 v[200:201], v194 offset:0xa00
	ds_read_b64_tr_b16 v[202:203], v194 offset:0xe00
	s_nop 0
	v_mfma_f32_32x32x16_bf16 v[0:15], v[68:71], v[40:43], v[0:15]
	v_mfma_f32_32x32x16_bf16 v[0:15], v[64:67], v[44:47], v[0:15]
	s_waitcnt lgkmcnt(6)
	v_mfma_f32_32x32x16_bf16 v[0:15], v[76:79], v[204:207], v[0:15]
	ds_read_b64_tr_b16 v[204:205], v194 offset:0x1200
	ds_read_b64_tr_b16 v[206:207], v194 offset:0x1600
	s_waitcnt lgkmcnt(6)
	v_mfma_f32_32x32x16_bf16 v[0:15], v[72:75], v[208:211], v[0:15]
	ds_read_b64_tr_b16 v[208:209], v194 offset:0x1a00
	ds_read_b64_tr_b16 v[210:211], v194 offset:0x1e00
	s_waitcnt lgkmcnt(0)
	v_mfma_f32_32x32x16_bf16 v[16:31], v[68:71], v[196:199], v[16:31]
	s_waitcnt vmcnt(3)
	s_waitcnt vmcnt(5)
	ds_write_b128 v192, v[138:141]
	s_waitcnt vmcnt(4)
	ds_write_b128 v193, v[142:145] offset:16384
	v_mfma_f32_32x32x16_bf16 v[16:31], v[64:67], v[200:203], v[16:31]
	v_mfma_f32_32x32x16_bf16 v[16:31], v[76:79], v[204:207], v[16:31]
	v_mfma_f32_32x32x16_bf16 v[16:31], v[72:75], v[208:211], v[16:31]
	s_and_saveexec_b64 s[4:5], s[40:41]
	s_cbranch_execz .LBB0_1096
	s_waitcnt vmcnt(3)
	ds_write_b128 v112, v[146:149] offset:16512
; #define SBAR() __builtin_amdgcn_sched_barrier(0)
; #define SLOAD(i, k0) do { st_[i].vs = *reinterpret_cast<const bf16x8*>(&Vh[(size_t)((k0) + sr) * LDK + sc]); \
;     st_[i].ks = *reinterpret_cast<const bf16x8*>(&Kh[(size_t)((k0) + sr) * LDK + sc]); \
;     if (DQ == 96) st_[i].kr = *reinterpret_cast<const bf16x8*>(&Kr[(size_t)((k0) + sr2) * 32 + sc2]); } while (0)
; #define SLOAD(i, k0) do { st_[i].vs = *reinterpret_cast<const bf16x8*>(&Vh[(size_t)((k0) + sr) * LDK + sc]); \
;     st_[i].ks = *reinterpret_cast<const bf16x8*>(&Kh[(size_t)((k0) + sr) * LDK + sc]); \
;     if (DQ == 96) st_[i].kr = *reinterpret_cast<const bf16x8*>(&Kr[(size_t)((k0) + sr2) * 32 + sc2]); } while (0)
; template <int DQ>
; __device__ __forceinline__ void qkt(f32x16& p0, f32x16& p1, const char* Ks, const bf16x8* qr, const f32x16& ci, int r32, int hi) {
;     constexpr int KROW = ACfg<DQ>::KROW;
; #pragma unroll
;     for (int d0 = 0; d0 < ACfg<DQ>::ND; ++d0) { const int cb = (d0 * 16 + hi * 8) * 2;
;         bf16x8 b0 = *reinterpret_cast<const bf16x8*>(Ks + r32 * KROW + cb);
;         bf16x8 b1 = *reinterpret_cast<const bf16x8*>(Ks + (32 + r32) * KROW + cb);
;         p0 = __builtin_amdgcn_mfma_f32_32x32x16_bf16(b0, qr[d0], d0 == 0 ? ci : p0, 0, 0, 0);
;         p1 = __builtin_amdgcn_mfma_f32_32x32x16_bf16(b1, qr[d0], d0 == 0 ? ci : p1, 0, 0, 0); }
; }
; template <int DQ, bool WIN, int LDQ, int LDK> ...
;     ...
;         SBAR(); qkt<DQ>(pA0, pA1, K_lds, qr, minit, r32, hi);
;         finish(pB0, pB1); SBAR();
;         if (j + 3 < NT) SLOAD(SE, KBASE(j + 3)); SBAR();
;         pv(vb0 + SHM_V);
.LBB0_1096:
	s_or_b64 exec, exec, s[4:5]
	s_add_i32 s17, s17, 2
	v_exp_f32_e32 v195, v96
	v_mfma_f32_16x16x32_bf16 v[32:35], v[68:71], v[36:39], v[32:35]
	v_exp_f32_e32 v204, v97
	v_exp_f32_e32 v205, v98
	v_exp_f32_e32 v206, v99
	v_exp_f32_e32 v207, v100
	v_exp_f32_e32 v208, v101
	v_exp_f32_e32 v209, v102
	v_exp_f32_e32 v210, v103
	v_mfma_f32_16x16x32_bf16 v[32:35], v[64:67], v[36:39], v[32:35]
	v_exp_f32_e32 v211, v104
	v_exp_f32_e32 v212, v105
	v_exp_f32_e32 v213, v106
	v_exp_f32_e32 v214, v107
	v_exp_f32_e32 v215, v108
	v_exp_f32_e32 v216, v109
	v_exp_f32_e32 v217, v110
	v_mfma_f32_16x16x32_bf16 v[32:35], v[76:79], v[36:39], v[32:35]
	v_exp_f32_e32 v218, v111
	s_waitcnt lgkmcnt(0)
	s_barrier
	v_mfma_f32_16x16x32_bf16 v[32:35], v[72:75], v[36:39], v[32:35]
	ds_read_b64_tr_b16 v[40:41], v190 offset:0
	ds_read_b64_tr_b16 v[42:43], v190 offset:0x400
	ds_read_b64_tr_b16 v[44:45], v190 offset:0x800
	ds_read_b64_tr_b16 v[46:47], v190 offset:0xc00
	ds_read_b128 v[64:67], v191 offset:16384
	ds_read_b128 v[196:199], v191 offset:23040
	ds_read_b128 v[200:203], v191 offset:16416
	ds_read_b128 v[138:141], v191 offset:23072
	v_exp_f32_e32 v95, v95
	v_exp_f32_e32 v219, v88
	v_exp_f32_e32 v220, v89
	s_waitcnt lgkmcnt(2)
	v_mfma_f32_32x32x16_bf16 v[96:111], v[64:67], v[134:137], v[48:63]
	v_exp_f32_e32 v221, v90
	v_exp_f32_e32 v222, v91
	v_exp_f32_e32 v223, v92
	v_exp_f32_e32 v224, v93
	v_exp_f32_e32 v225, v94
	v_mfma_f32_32x32x16_bf16 v[64:79], v[196:199], v[134:137], v[48:63]
	ds_read_b128 v[142:145], v191 offset:16448
	ds_read_b128 v[196:199], v191 offset:23104
	s_waitcnt lgkmcnt(2)
	v_mfma_f32_32x32x16_bf16 v[96:111], v[200:203], v[130:133], v[96:111]
	v_mfma_f32_32x32x16_bf16 v[64:79], v[138:141], v[130:133], v[64:79]
	ds_read_b128 v[200:203], v191 offset:16480
	ds_read_b128 v[138:141], v191 offset:23136
	s_waitcnt lgkmcnt(2)
	v_mfma_f32_32x32x16_bf16 v[96:111], v[142:145], v[126:129], v[96:111]
	v_mfma_f32_32x32x16_bf16 v[64:79], v[196:199], v[126:129], v[64:79]
	ds_read_b128 v[142:145], v191 offset:16512
	ds_read_b128 v[196:199], v191 offset:23168
	s_waitcnt lgkmcnt(2)
	v_mfma_f32_32x32x16_bf16 v[96:111], v[200:203], v[122:125], v[96:111]
	v_mfma_f32_32x32x16_bf16 v[64:79], v[138:141], v[122:125], v[64:79]
	ds_read_b128 v[200:203], v191 offset:16544
	ds_read_b128 v[138:141], v191 offset:23200
	s_waitcnt lgkmcnt(2)
	v_mfma_f32_32x32x16_bf16 v[96:111], v[142:145], v[118:121], v[96:111]
	v_mfma_f32_32x32x16_bf16 v[64:79], v[196:199], v[118:121], v[64:79]
	s_waitcnt lgkmcnt(0)
	v_mfma_f32_32x32x16_bf16 v[96:111], v[200:203], v[114:117], v[96:111]
	v_exp_f32_e32 v196, v80
	v_exp_f32_e32 v197, v81
	v_exp_f32_e32 v198, v82
	v_exp_f32_e32 v199, v83
	v_cvt_pk_bf16_f32 v80, v195, v204
	v_cvt_pk_bf16_f32 v81, v205, v206
	v_cvt_pk_bf16_f32 v82, v207, v208
	v_mfma_f32_32x32x16_bf16 v[64:79], v[138:141], v[114:117], v[64:79]
	v_exp_f32_e32 v200, v84
	v_exp_f32_e32 v201, v85
	v_exp_f32_e32 v202, v86
	v_exp_f32_e32 v203, v87
	v_cvt_pk_bf16_f32 v83, v209, v210
	v_cvt_pk_bf16_f32 v84, v211, v212
	v_cvt_pk_bf16_f32 v85, v213, v214
	v_cvt_pk_bf16_f32 v86, v215, v216
	v_cvt_pk_bf16_f32 v87, v217, v218
	v_cvt_pk_bf16_f32 v88, v196, v197
	v_cvt_pk_bf16_f32 v89, v198, v199
	v_cvt_pk_bf16_f32 v90, v200, v201
	v_cvt_pk_bf16_f32 v91, v202, v203
	v_cvt_pk_bf16_f32 v92, v219, v220
	v_cvt_pk_bf16_f32 v93, v221, v222
	v_cvt_pk_bf16_f32 v94, v223, v224
	v_cvt_pk_bf16_f32 v95, v225, v95
	s_cmpk_gt_u32 s17, 0x7c
	s_cselect_b64 s[4:5], -1, 0
	s_and_b64 vcc, exec, s[4:5]
	s_cbranch_vccnz .LBB0_1098
	v_add_co_u32_e32 v142, vcc, 0x21900000, v168
	s_waitcnt vmcnt(3)
	v_lshl_add_u64 v[146:147], s[26:27], 0, v[162:163]
	v_addc_co_u32_e32 v143, vcc, 0, v169, vcc
	global_load_dwordx4 v[138:141], v[142:143], off offset:128
	s_nop 0
	global_load_dwordx4 v[142:145], v[142:143], off
	s_nop 0
	global_load_dwordx4 v[146:149], v[146:147], off
